# g1 + sliding-window key-norm gains parked in LDS once per tile, key rope rows requested at staging top
# speedup vs baseline: 1.0204x; 1.0004x over previous
.LBB0_176:
	s_and_b32 s0, s57, 7
	v_writelane_b32 v243, s57, 7
	s_ashr_i32 s1, s57, 3
	v_writelane_b32 v243, s0, 8
	s_lshl_b32 s0, s0, 12
	s_lshl_b32 s2, s1, 7
	v_mov_b32_e32 v36, v0
	s_add_i32 s20, s2, s0
	s_barrier
	v_readlane_b32 s94, v244, 20
	v_readlane_b32 s95, v244, 21
	v_and_b32_e32 v4, 63, v0
	v_lshlrev_b32_e32 v4, 2, v4
	s_nop 4
	global_load_dword v129, v4, s[94:95]
	s_cmp_gt_i32 s1, 0
	v_ashrrev_i32_e32 v50, 1, v36
	s_cselect_b64 s[22:23], -1, 0
	v_cmp_lt_i32_e32 vcc, s84, v50
	v_writelane_b32 v243, s1, 9
	s_or_b64 s[0:1], s[22:23], vcc
	v_and_b32_e32 v54, 1, v36
	v_writelane_b32 v243, s0, 10
	v_ashrrev_i32_e32 v51, 31, v50
	v_lshlrev_b32_e32 v2, 5, v54
	v_writelane_b32 v243, s1, 11
	s_xor_b64 s[0:1], s[0:1], -1
	s_and_saveexec_b64 s[4:5], s[0:1]
	s_xor_b64 s[0:1], exec, s[4:5]
	s_ashr_i32 s21, s20, 31
	v_lshl_add_u64 v[4:5], v[50:51], 0, s[20:21]
	v_lshlrev_b32_e32 v2, 5, v54
	v_mad_u64_u32 v[52:53], s[4:5], v4, s92, 0
	v_mad_i32_i24 v53, v5, s92, v53
	v_mov_b32_e32 v55, v2
	v_mov_b64_e32 v[48:49], v[2:3]
	s_or_saveexec_b64 s[0:1], s[0:1]
	v_mov_b32_e32 v110, 0
	s_mov_b32 s33, 0
	v_mov_b32_e32 v24, 0
	v_mov_b32_e32 v25, 0
	v_mov_b32_e32 v26, 0
	v_mov_b32_e32 v27, 0
	v_mov_b32_e32 v28, 0
	v_mov_b32_e32 v29, 0
	v_mov_b32_e32 v30, 0
	v_mov_b32_e32 v31, 0
	v_mov_b32_e32 v32, 0
	v_mov_b32_e32 v33, 0
	v_mov_b32_e32 v34, 0
	v_mov_b32_e32 v35, 0
	v_mov_b32_e32 v20, 0
	v_mov_b32_e32 v21, 0
	v_mov_b32_e32 v22, 0
	v_mov_b32_e32 v23, 0
	v_mov_b32_e32 v4, 0
	v_mov_b32_e32 v5, 0
	v_mov_b32_e32 v6, 0
	v_mov_b32_e32 v7, 0
	v_mov_b32_e32 v12, 0
	v_mov_b32_e32 v13, 0
	v_mov_b32_e32 v14, 0
	v_mov_b32_e32 v15, 0
	v_mov_b32_e32 v8, 0
	v_mov_b32_e32 v9, 0
	v_mov_b32_e32 v10, 0
	v_mov_b32_e32 v11, 0
	v_mov_b32_e32 v16, 0
	v_mov_b32_e32 v17, 0
	v_mov_b32_e32 v18, 0
	v_mov_b32_e32 v19, 0
	s_xor_b64 exec, exec, s[0:1]
	s_cbranch_execz .LBB0_180
	s_ashr_i32 s21, s20, 31
	v_lshl_add_u64 v[38:39], v[50:51], 0, s[20:21]
	v_mov_b64_e32 v[4:5], s[88:89]
	v_mad_u64_u32 v[4:5], s[4:5], v38, s92, v[4:5]
	v_mad_i32_i24 v5, v39, s92, v5
	v_lshlrev_b32_e32 v6, 6, v54
	v_mov_b32_e32 v7, v3
	s_mov_b32 s4, 0xfff70b00
	v_lshl_add_u64 v[4:5], v[4:5], 0, v[6:7]
	s_mov_b32 s5, -1
	v_lshl_add_u64 v[20:21], v[4:5], 0, s[4:5]
	s_mov_b32 s4, 0xfff70a00
	s_mov_b32 s3, 0xfff71000
	s_mov_b32 s5, -1
	v_add_co_u32_e32 v14, vcc, s3, v4
	v_lshl_add_u64 v[12:13], v[4:5], 0, s[4:5]
	s_nop 0
	v_addc_co_u32_e32 v15, vcc, -1, v5, vcc
	global_load_dwordx4 v[8:11], v[12:13], off offset:32
	global_load_dwordx4 v[16:19], v[12:13], off offset:48
	global_load_dwordx4 v[4:7], v[14:15], off offset:-1536
	global_load_dwordx4 v[24:27], v[14:15], off offset:-1280
	global_load_dwordx4 v[28:31], v[20:21], off offset:16
	global_load_dwordx4 v[32:35], v[20:21], off offset:32
	s_nop 0
	global_load_dwordx4 v[12:15], v[12:13], off offset:16
	s_nop 0
	global_load_dwordx4 v[20:23], v[20:21], off offset:48
	v_mad_u64_u32 v[52:53], s[4:5], v38, s92, 0
	v_mad_i32_i24 v53, v39, s92, v53
	v_mov_b64_e32 v[48:49], v[2:3]
	v_mov_b32_e32 v55, v2
.LBB0_180:
	s_or_b64 exec, exec, s[0:1]
	v_and_b32_e32 v37, 64, v182
	v_ashrrev_i32_e32 v59, 6, v36
	v_bfe_u32 v51, v36, 4, 2
	v_and_b32_e32 v56, 15, v36
	v_xor_b32_e32 v36, 1, v182
	v_add_u32_e32 v37, 64, v37
	v_cmp_lt_i32_e32 vcc, v36, v37
	v_lshlrev_b32_e32 v2, 4, v59
	v_min_i32_e32 v57, 6, v59
	v_and_b32_e32 v57, -2, v57
	v_cndmask_b32_e32 v61, v182, v36, vcc
	v_xor_b32_e32 v36, 16, v182
	v_cmp_lt_i32_e32 vcc, v36, v37
	v_lshlrev_b32_e32 v111, 2, v51
	v_lshlrev_b32_e32 v68, 4, v57
	v_cndmask_b32_e32 v66, v182, v36, vcc
	v_xor_b32_e32 v36, 32, v182
	v_cmp_lt_i32_e32 vcc, v36, v37
	v_or_b32_e32 v38, v68, v111
	s_movk_i32 s3, 0x7e
	v_cndmask_b32_e32 v67, v182, v36, vcc
	v_cmp_eq_u32_e32 vcc, 1, v51
	v_or_b32_e32 v39, 2, v38
	v_add_u32_e32 v69, 16, v68
	v_cndmask_b32_e64 v36, 0, 1.0, vcc
	v_cmp_ne_u32_e32 vcc, 0, v51
	v_add_u32_e32 v70, 2, v57
	v_lshlrev_b32_e32 v71, 4, v70
	v_cndmask_b32_e32 v114, -1.0, v36, vcc
	v_or_b32_e32 v36, v2, v56
	v_add_u32_e32 v37, 0x80, v36
	v_cmp_gt_i32_e32 vcc, v38, v36
	v_cmp_le_i32_e64 s[0:1], v38, v37
	s_and_b64 s[0:1], vcc, s[0:1]
	v_cmp_lt_i32_e32 vcc, s84, v38
	s_or_b64 s[4:5], s[22:23], vcc
	s_and_b64 s[0:1], s[0:1], s[4:5]
	v_cmp_ge_i32_e32 vcc, v38, v36
	v_cmp_lt_i32_e64 s[4:5], v38, v37
	s_and_b64 s[4:5], vcc, s[4:5]
	v_cmp_lt_i32_e32 vcc, s3, v38
	v_writelane_b32 v243, s0, 12
	s_or_b64 s[6:7], s[22:23], vcc
	v_cmp_gt_i32_e32 vcc, v39, v36
	v_writelane_b32 v243, s1, 13
	s_and_b64 s[0:1], s[4:5], s[6:7]
	v_cmp_le_i32_e64 s[6:7], v39, v37
	s_and_b64 s[6:7], vcc, s[6:7]
	v_cmp_lt_i32_e32 vcc, s84, v39
	v_writelane_b32 v243, s0, 14
	s_or_b64 s[8:9], s[22:23], vcc
	v_or_b32_e32 v38, 3, v38
	v_writelane_b32 v243, s1, 15
	s_and_b64 s[0:1], s[6:7], s[8:9]
	v_cmp_gt_i32_e32 vcc, v38, v36
	v_cmp_le_i32_e64 s[8:9], v38, v37
	s_and_b64 s[8:9], vcc, s[8:9]
	v_cmp_lt_i32_e32 vcc, s84, v38
	v_writelane_b32 v243, s0, 16
	s_or_b64 s[10:11], s[22:23], vcc
	v_or_b32_e32 v38, v69, v111
	v_writelane_b32 v243, s1, 17
	s_and_b64 s[0:1], s[8:9], s[10:11]
	v_cmp_gt_i32_e32 vcc, v38, v36
	v_cmp_le_i32_e64 s[10:11], v38, v37
	s_and_b64 s[10:11], vcc, s[10:11]
	v_cmp_lt_i32_e32 vcc, s84, v38
	v_writelane_b32 v243, s0, 18
	s_or_b64 s[12:13], s[22:23], vcc
	v_cmp_ge_i32_e32 vcc, v38, v36
	v_writelane_b32 v243, s1, 19
	s_and_b64 s[0:1], s[10:11], s[12:13]
	v_cmp_lt_i32_e64 s[12:13], v38, v37
	s_and_b64 s[12:13], vcc, s[12:13]
	v_cmp_lt_i32_e32 vcc, s3, v38
	v_writelane_b32 v243, s0, 20
	s_or_b64 s[14:15], s[22:23], vcc
	v_or_b32_e32 v39, 2, v38
	v_writelane_b32 v243, s1, 21
	s_and_b64 s[0:1], s[12:13], s[14:15]
	v_cmp_gt_i32_e32 vcc, v39, v36
	v_cmp_le_i32_e64 s[14:15], v39, v37
	s_and_b64 s[14:15], vcc, s[14:15]
	v_cmp_lt_i32_e32 vcc, s84, v39
	v_writelane_b32 v243, s0, 22
	s_or_b64 s[16:17], s[22:23], vcc
	v_or_b32_e32 v38, 3, v38
	v_writelane_b32 v243, s1, 23
	s_and_b64 s[0:1], s[14:15], s[16:17]
	v_cmp_gt_i32_e32 vcc, v38, v36
	v_cmp_le_i32_e64 s[16:17], v38, v37
	s_and_b64 s[16:17], vcc, s[16:17]
	v_cmp_lt_i32_e32 vcc, s84, v38
	v_writelane_b32 v243, s0, 24
	s_or_b64 s[18:19], s[22:23], vcc
	v_or_b32_e32 v38, v71, v111
	v_writelane_b32 v243, s1, 25
	s_and_b64 s[0:1], s[16:17], s[18:19]
	v_cmp_gt_i32_e32 vcc, v38, v36
	v_cmp_le_i32_e64 s[18:19], v38, v37
	s_and_b64 s[18:19], vcc, s[18:19]
	v_cmp_lt_i32_e32 vcc, s84, v38
	v_writelane_b32 v243, s0, 26
	s_mov_b32 s4, s20
	s_or_b64 s[20:21], s[22:23], vcc
	v_writelane_b32 v243, s1, 27
	s_and_b64 s[0:1], s[18:19], s[20:21]
	v_cmp_ge_i32_e32 vcc, v38, v36
	v_cmp_lt_i32_e64 s[20:21], v38, v37
	s_and_b64 s[20:21], vcc, s[20:21]
	v_cmp_lt_i32_e32 vcc, s3, v38
	s_mov_b64 s[6:7], s[22:23]
	s_or_b64 s[22:23], s[22:23], vcc
	v_or_b32_e32 v39, 2, v38
	s_and_b64 s[20:21], s[20:21], s[22:23]
	v_cmp_gt_i32_e32 vcc, v39, v36
	v_cmp_le_i32_e64 s[22:23], v39, v37
	s_and_b64 s[22:23], vcc, s[22:23]
	v_cmp_lt_i32_e32 vcc, s84, v39
	s_or_b64 s[24:25], s[6:7], vcc
	v_or_b32_e32 v38, 3, v38
	s_and_b64 s[22:23], s[22:23], s[24:25]
	v_cmp_gt_i32_e32 vcc, v38, v36
	v_cmp_le_i32_e64 s[24:25], v38, v37
	v_add_u32_e32 v72, 48, v68
	s_and_b64 s[24:25], vcc, s[24:25]
	v_cmp_lt_i32_e32 vcc, s84, v38
	s_or_b64 s[26:27], s[6:7], vcc
	v_or_b32_e32 v38, v72, v111
	s_and_b64 s[24:25], s[24:25], s[26:27]
	v_cmp_gt_i32_e32 vcc, v38, v36
	v_cmp_le_i32_e64 s[26:27], v38, v37
	s_and_b64 s[26:27], vcc, s[26:27]
	v_cmp_lt_i32_e32 vcc, s84, v38
	s_or_b64 s[28:29], s[6:7], vcc
	s_and_b64 s[26:27], s[26:27], s[28:29]
	v_cmp_ge_i32_e32 vcc, v38, v36
	v_cmp_lt_i32_e64 s[28:29], v38, v37
	s_and_b64 s[28:29], vcc, s[28:29]
	v_cmp_lt_i32_e32 vcc, s3, v38
	s_or_b64 s[30:31], s[6:7], vcc
	v_or_b32_e32 v39, 2, v38
	s_and_b64 s[28:29], s[28:29], s[30:31]
	v_cmp_gt_i32_e32 vcc, v39, v36
	v_cmp_le_i32_e64 s[30:31], v39, v37
	s_and_b64 s[30:31], vcc, s[30:31]
	v_cmp_lt_i32_e32 vcc, s84, v39
	s_or_b64 s[34:35], s[6:7], vcc
	v_or_b32_e32 v38, 3, v38
	v_add_u32_e32 v73, 4, v57
	s_and_b64 s[30:31], s[30:31], s[34:35]
	v_cmp_gt_i32_e32 vcc, v38, v36
	v_cmp_le_i32_e64 s[34:35], v38, v37
	v_lshlrev_b32_e32 v74, 4, v73
	s_and_b64 s[34:35], vcc, s[34:35]
	v_cmp_lt_i32_e32 vcc, s84, v38
	s_or_b64 s[36:37], s[6:7], vcc
	v_or_b32_e32 v38, v74, v111
	s_and_b64 s[34:35], s[34:35], s[36:37]
	v_cmp_gt_i32_e32 vcc, v38, v36
	v_cmp_le_i32_e64 s[36:37], v38, v37
	s_and_b64 s[36:37], vcc, s[36:37]
	v_cmp_lt_i32_e32 vcc, s84, v38
	s_or_b64 s[38:39], s[6:7], vcc
	s_and_b64 s[36:37], s[36:37], s[38:39]
	v_cmp_ge_i32_e32 vcc, v38, v36
	v_cmp_lt_i32_e64 s[38:39], v38, v37
	s_and_b64 s[38:39], vcc, s[38:39]
	v_cmp_lt_i32_e32 vcc, s3, v38
	s_or_b64 s[40:41], s[6:7], vcc
	v_or_b32_e32 v39, 2, v38
	s_and_b64 s[38:39], s[38:39], s[40:41]
	v_cmp_gt_i32_e32 vcc, v39, v36
	v_cmp_le_i32_e64 s[40:41], v39, v37
	s_and_b64 s[40:41], vcc, s[40:41]
	v_cmp_lt_i32_e32 vcc, s84, v39
	s_or_b64 s[42:43], s[6:7], vcc
	v_or_b32_e32 v38, 3, v38
	s_and_b64 s[40:41], s[40:41], s[42:43]
	v_cmp_gt_i32_e32 vcc, v38, v36
	v_cmp_le_i32_e64 s[42:43], v38, v37
	v_add_u32_e32 v75, 0x50, v68
	s_and_b64 s[42:43], vcc, s[42:43]
	v_cmp_lt_i32_e32 vcc, s84, v38
	s_or_b64 s[44:45], s[6:7], vcc
	v_or_b32_e32 v38, v75, v111
	s_and_b64 s[42:43], s[42:43], s[44:45]
	v_cmp_gt_i32_e32 vcc, v38, v36
	v_cmp_le_i32_e64 s[44:45], v38, v37
	s_and_b64 s[44:45], vcc, s[44:45]
	v_cmp_lt_i32_e32 vcc, s84, v38
	s_or_b64 s[46:47], s[6:7], vcc
	s_and_b64 s[44:45], s[44:45], s[46:47]
	v_cmp_ge_i32_e32 vcc, v38, v36
	v_cmp_lt_i32_e64 s[46:47], v38, v37
	s_and_b64 s[46:47], vcc, s[46:47]
	v_cmp_lt_i32_e32 vcc, s3, v38
	s_or_b64 s[48:49], s[6:7], vcc
	v_or_b32_e32 v39, 2, v38
	s_and_b64 s[46:47], s[46:47], s[48:49]
	v_cmp_gt_i32_e32 vcc, v39, v36
	v_cmp_le_i32_e64 s[48:49], v39, v37
	s_and_b64 s[48:49], vcc, s[48:49]
	v_cmp_lt_i32_e32 vcc, s84, v39
	s_or_b64 s[50:51], s[6:7], vcc
	v_or_b32_e32 v38, 3, v38
	v_add_u32_e32 v76, 6, v57
	s_and_b64 s[48:49], s[48:49], s[50:51]
	v_cmp_gt_i32_e32 vcc, v38, v36
	v_cmp_le_i32_e64 s[50:51], v38, v37
	v_lshlrev_b32_e32 v77, 4, v76
	s_and_b64 s[50:51], vcc, s[50:51]
	v_cmp_lt_i32_e32 vcc, s84, v38
	s_or_b64 s[52:53], s[6:7], vcc
	v_or_b32_e32 v38, v77, v111
	s_and_b64 s[50:51], s[50:51], s[52:53]
	v_cmp_gt_i32_e32 vcc, v38, v36
	v_cmp_le_i32_e64 s[52:53], v38, v37
	s_and_b64 s[52:53], vcc, s[52:53]
	v_cmp_lt_i32_e32 vcc, s84, v38
	s_or_b64 s[54:55], s[6:7], vcc
	s_and_b64 s[52:53], s[52:53], s[54:55]
	v_cmp_ge_i32_e32 vcc, v38, v36
	v_cmp_lt_i32_e64 s[54:55], v38, v37
	s_and_b64 s[54:55], vcc, s[54:55]
	v_cmp_lt_i32_e32 vcc, s3, v38
	s_or_b64 s[56:57], s[6:7], vcc
	v_or_b32_e32 v39, 2, v38
	s_and_b64 s[54:55], s[54:55], s[56:57]
	v_cmp_gt_i32_e32 vcc, v39, v36
	v_cmp_le_i32_e64 s[56:57], v39, v37
	s_and_b64 s[56:57], vcc, s[56:57]
	v_cmp_lt_i32_e32 vcc, s84, v39
	s_or_b64 s[58:59], s[6:7], vcc
	v_or_b32_e32 v38, 3, v38
	s_and_b64 s[56:57], s[56:57], s[58:59]
	v_cmp_gt_i32_e32 vcc, v38, v36
	v_cmp_le_i32_e64 s[58:59], v38, v37
	v_add_u32_e32 v78, 0x70, v68
	s_and_b64 s[58:59], vcc, s[58:59]
	v_cmp_lt_i32_e32 vcc, s84, v38
	s_or_b64 s[60:61], s[6:7], vcc
	v_or_b32_e32 v38, v78, v111
	s_and_b64 s[58:59], s[58:59], s[60:61]
	v_cmp_gt_i32_e32 vcc, v38, v36
	v_cmp_le_i32_e64 s[60:61], v38, v37
	s_and_b64 s[60:61], vcc, s[60:61]
	v_cmp_lt_i32_e32 vcc, s84, v38
	s_or_b64 s[62:63], s[6:7], vcc
	s_and_b64 s[60:61], s[60:61], s[62:63]
	v_cmp_ge_i32_e32 vcc, v38, v36
	v_cmp_lt_i32_e64 s[62:63], v38, v37
	s_and_b64 s[62:63], vcc, s[62:63]
	v_cmp_lt_i32_e32 vcc, s3, v38
	s_or_b64 s[64:65], s[6:7], vcc
	v_or_b32_e32 v39, 2, v38
	s_and_b64 s[62:63], s[62:63], s[64:65]
	v_cmp_gt_i32_e32 vcc, v39, v36
	v_cmp_le_i32_e64 s[64:65], v39, v37
	s_and_b64 s[64:65], vcc, s[64:65]
	v_cmp_lt_i32_e32 vcc, s84, v39
	s_or_b64 s[66:67], s[6:7], vcc
	v_or_b32_e32 v38, 3, v38
	s_and_b64 s[64:65], s[64:65], s[66:67]
	v_cmp_gt_i32_e32 vcc, v38, v36
	v_cmp_le_i32_e64 s[66:67], v38, v37
	v_add_u32_e32 v79, 8, v57
	s_and_b64 s[66:67], vcc, s[66:67]
	v_cmp_lt_i32_e32 vcc, s84, v38
	v_lshlrev_b32_e32 v98, 4, v79
	s_or_b64 s[68:69], s[6:7], vcc
	v_or_b32_e32 v38, v98, v111
	s_and_b64 s[66:67], s[66:67], s[68:69]
	v_cmp_gt_i32_e32 vcc, v38, v36
	v_cmp_le_i32_e64 s[68:69], v38, v37
	s_and_b64 s[68:69], vcc, s[68:69]
	v_cmp_lt_i32_e32 vcc, s84, v38
	s_or_b64 s[70:71], s[6:7], vcc
	s_and_b64 s[68:69], s[68:69], s[70:71]
	v_cmp_ge_i32_e32 vcc, v38, v36
	v_cmp_lt_i32_e64 s[70:71], v38, v37
	s_and_b64 s[70:71], vcc, s[70:71]
	v_cmp_lt_i32_e32 vcc, s3, v38
	s_or_b64 s[72:73], s[6:7], vcc
	v_or_b32_e32 v39, 2, v38
	s_and_b64 s[70:71], s[70:71], s[72:73]
	v_cmp_gt_i32_e32 vcc, v39, v36
	v_cmp_le_i32_e64 s[72:73], v39, v37
	s_and_b64 s[72:73], vcc, s[72:73]
	v_cmp_lt_i32_e32 vcc, s84, v39
	s_or_b64 s[74:75], s[6:7], vcc
	v_or_b32_e32 v38, 3, v38
	s_and_b64 s[72:73], s[72:73], s[74:75]
	v_cmp_gt_i32_e32 vcc, v38, v36
	v_cmp_le_i32_e64 s[74:75], v38, v37
	s_and_b64 s[74:75], vcc, s[74:75]
	v_cmp_lt_i32_e32 vcc, s84, v38
	v_add_u32_e32 v99, 0x90, v68
	s_or_b64 s[76:77], s[6:7], vcc
	v_or_b32_e32 v38, v99, v111
	s_and_b64 s[74:75], s[74:75], s[76:77]
	v_cmp_gt_i32_e32 vcc, v38, v36
	v_cmp_le_i32_e64 s[76:77], v38, v37
	s_and_b64 s[76:77], vcc, s[76:77]
	v_cmp_lt_i32_e32 vcc, s84, v38
	s_or_b64 s[78:79], s[6:7], vcc
	s_and_b64 s[76:77], s[76:77], s[78:79]
	v_cmp_ge_i32_e32 vcc, v38, v36
	v_cmp_lt_i32_e64 s[78:79], v38, v37
	s_and_b64 s[78:79], vcc, s[78:79]
	v_cmp_lt_i32_e32 vcc, s3, v38
	s_or_b64 s[80:81], s[6:7], vcc
	v_or_b32_e32 v39, 2, v38
	s_and_b64 s[78:79], s[78:79], s[80:81]
	v_cmp_gt_i32_e32 vcc, v39, v36
	v_cmp_le_i32_e64 s[80:81], v39, v37
	s_and_b64 s[80:81], vcc, s[80:81]
	v_cmp_lt_i32_e32 vcc, s84, v39
	s_or_b64 s[82:83], s[6:7], vcc
	v_writelane_b32 v243, s6, 28
	v_or_b32_e32 v38, 3, v38
	v_add_u32_e32 v64, s2, v50
	v_writelane_b32 v243, s7, 29
	v_add_u32_e32 v90, s2, v2
	s_mov_b32 s2, s4
	v_add_u32_e32 v2, s4, v2
	s_and_b64 s[80:81], s[80:81], s[82:83]
	v_cmp_gt_i32_e32 vcc, v38, v36
	v_cmp_le_i32_e64 s[82:83], v38, v37
	v_writelane_b32 v243, s2, 30
	v_or_b32_e32 v80, v2, v56
	v_lshlrev_b32_e32 v58, 3, v51
	v_mov_b64_e32 v[36:37], s[88:89]
	v_writelane_b32 v243, s3, 31
	v_mad_i64_i32 v[82:83], s[2:3], v80, s92, v[36:37]
	v_lshlrev_b32_e32 v2, 4, v51
	v_bitop3_b32 v60, v58, 8, v58 bitop3:0xc
	v_lshl_add_u64 v[36:37], v[82:83], 0, v[2:3]
	v_lshlrev_b32_e32 v44, 1, v60
	v_mov_b32_e32 v45, v3
	s_and_b64 s[82:83], vcc, s[82:83]
	v_cmp_lt_i32_e32 vcc, s84, v38
	global_load_dwordx4 v[40:43], v[36:37], off offset:2048
	s_nop 0
	global_load_dwordx4 v[36:39], v[36:37], off offset:2112
	v_lshl_add_u64 v[44:45], v[82:83], 0, v[44:45]
	global_load_dwordx4 v[44:47], v[44:45], off offset:2048
	v_mul_lo_u32 v59, v59, s93
	v_add_u32_e32 v59, s96, v59
	v_mul_u32_u24_e32 v100, 0x210, v56
	v_add3_u32 v109, v59, v100, v58
	v_mul_lo_u32 v59, v50, s97
	v_add_u32_e32 v62, 0, v59
	v_lshl_add_u32 v115, v55, 1, v62
	v_mad_u64_u32 v[62:63], s[2:3], v50, s98, v[62:63]
	v_lshl_add_u64 v[52:53], s[88:89], 0, v[52:53]
	s_mov_b32 s2, 0xfff70b80
	v_lshl_add_u64 v[52:53], v[48:49], 1, v[52:53]
	s_mov_b32 s3, -1
	v_lshl_add_u64 v[86:87], v[52:53], 0, s[2:3]
	s_mov_b32 s2, 0xfff70a80
	s_mov_b32 s3, -1
	v_max_i32_e32 v50, 0x80, v64
	v_lshl_add_u64 v[88:89], v[52:53], 0, s[2:3]
	v_or_b32_e32 v52, v90, v56
	v_lshl_add_u32 v64, v50, 4, v183
	v_lshlrev_b32_e32 v52, 4, v52
	s_or_b64 s[84:85], s[6:7], vcc
	v_ashrrev_i32_e32 v65, 31, v64
	v_ashrrev_i32_e32 v53, 31, v52
	s_and_b64 s[82:83], s[82:83], s[84:85]
	v_lshl_add_u64 v[84:85], v[64:65], 2, s[86:87]
	v_lshl_add_u64 v[90:91], v[52:53], 2, s[86:87]
	s_mov_b32 s2, s96
	v_readlane_b32 s84, v244, 10
	v_readlane_b32 s88, v244, 14
	v_readlane_b32 s89, v244, 15
	v_readlane_b32 s90, v244, 16
	v_readlane_b32 s91, v244, 17
	v_readlane_b32 s92, v244, 18
	v_readlane_b32 s93, v244, 19
	v_readlane_b32 s94, v244, 20
	v_readlane_b32 s95, v244, 21
	v_readlane_b32 s96, v244, 22
	v_readlane_b32 s97, v244, 23
	s_mov_b64 s[8:9], s[88:89]
	v_add_u32_e32 v52, 0, v2
	s_mov_b64 s[12:13], s[92:93]
	v_lshlrev_b32_e32 v2, 5, v51
	v_lshl_add_u64 v[94:95], s[12:13], 0, v[2:3]
	v_lshlrev_b32_e32 v2, 2, v60
	s_mov_b64 s[10:11], s[90:91]
	s_mov_b64 s[14:15], s[94:95]
	s_mov_b64 s[16:17], s[96:97]
	s_movk_i32 s97, 0x90
	v_lshl_add_u64 v[96:97], s[12:13], 0, v[2:3]
	v_or_b32_e32 v2, v68, v56
	v_lshlrev_b32_e32 v92, 2, v48
	v_add_u32_e32 v92, 0x21d00, v92
	v_mul_lo_u32 v48, v2, s97
	v_or_b32_e32 v2, v69, v56
	v_mul_lo_u32 v49, v2, s97
	v_or_b32_e32 v2, v71, v56
	v_mul_lo_u32 v55, v2, s97
	v_or_b32_e32 v2, v72, v56
	v_mul_lo_u32 v59, v2, s97
	v_or_b32_e32 v2, v74, v56
	v_mul_lo_u32 v61, v2, s97
	v_or_b32_e32 v2, v75, v56
	v_mul_lo_u32 v63, v2, s97
	v_or_b32_e32 v2, v77, v56
	v_mul_lo_u32 v64, v2, s97
	v_or_b32_e32 v2, v78, v56
	v_mul_lo_u32 v65, v2, s97
	v_or_b32_e32 v2, v98, v56
	v_lshlrev_b32_e32 v128, 2, v66
	v_mov_b32_e32 v53, v52
	v_mul_lo_u32 v66, v2, s97
	v_or_b32_e32 v2, v99, v56
	v_mul_u32_u24_e32 v50, 0x4200, v54
	v_lshlrev_b32_e32 v113, 2, v67
	v_readlane_b32 s85, v244, 11
	v_readlane_b32 s86, v244, 12
	v_readlane_b32 s87, v244, 13
	v_readlane_b32 s98, v244, 24
	v_mul_lo_u32 v56, v2, s97
	v_lshl_add_u32 v57, v57, 5, v53
	v_lshl_add_u32 v67, v70, 5, v53
	v_lshl_add_u32 v68, v73, 5, v53
	v_lshl_add_u32 v69, v76, 5, v53
	v_lshl_add_u32 v53, v79, 5, v53
	v_ashrrev_i32_e32 v81, 31, v80
	v_readlane_b32 s99, v244, 25
	s_movk_i32 s98, 0xff72
	s_mov_b32 s96, s2
	s_movk_i32 s93, 0x2100
	s_movk_i32 s92, 0x1200
	v_and_b32_e32 v241, 24, v62
	v_and_b32_e32 v242, 32, v62
	v_and_b32_e32 v62, 0xffffffc7, v62
	v_lshlrev_b32_e32 v241, 1, v241
	v_lshrrev_b32_e32 v242, 2, v242
	v_or3_b32 v62, v62, v241, v242
	v_add_u32_e32 v116, v62, v50
	v_lshlrev_b32_e32 v2, 1, v60
	v_lshlrev_b32_e32 v98, 1, v58
	v_add_u32_e32 v117, v52, v48
	v_add_u32_e32 v118, v52, v49
	v_add_u32_e32 v119, v52, v55
	v_add_u32_e32 v120, v52, v59
	v_add_u32_e32 v121, v52, v61
	v_add_u32_e32 v122, v52, v63
	v_add_u32_e32 v123, v52, v64
	v_add_u32_e32 v124, v52, v65
	v_add_u32_e32 v125, v52, v66
	v_add_u32_e32 v126, v52, v56
	v_add_u32_e32 v127, v57, v100
	v_add_u32_e32 v130, v67, v100
	v_add_u32_e32 v131, v68, v100
	v_add_u32_e32 v132, v69, v100
	v_add_u32_e32 v133, v53, v100
	v_cmp_eq_u32_e64 s[84:85], 0, v54
	v_cmp_gt_u32_e64 s[86:87], 2, v51
	global_load_dwordx4 v[224:227], v[94:95], off
	global_load_dwordx4 v[228:231], v[94:95], off offset:16
	global_load_dwordx4 v[232:235], v[94:95], off offset:128
	global_load_dwordx4 v[236:239], v[94:95], off offset:144
	global_load_dwordx4 v[248:251], v[90:91], off offset:32
	global_load_dwordx4 v[252:255], v[90:91], off offset:48
	v_mov_b32_e32 v240, 1.0
	v_mov_b32_e32 v241, 1.0
	v_mov_b32_e32 v242, 1.0
	v_mov_b32_e32 v245, 1.0
	v_mov_b32_e32 v246, 1.0
	v_mov_b32_e32 v247, 1.0
	v_mov_b32_e32 v217, 1.0
	v_mov_b32_e32 v219, 1.0
	s_and_saveexec_b64 vcc, s[86:87]
	global_load_dword v240, v[90:91], off
	global_load_dword v241, v[90:91], off offset:4
	global_load_dword v242, v[90:91], off offset:8
	global_load_dword v245, v[90:91], off offset:12
	global_load_dword v246, v[90:91], off offset:16
	global_load_dword v247, v[90:91], off offset:20
	global_load_dword v217, v[90:91], off offset:24
	global_load_dword v219, v[90:91], off offset:28
	s_or_b64 exec, exec, vcc
	s_waitcnt vmcnt(17)
	v_and_b32_e32 v90, 63, v0
	v_lshlrev_b32_e32 v90, 2, v90
	v_add_u32_e32 v90, 0x21d00, v90
	ds_write_b32 v90, v129
	s_waitcnt lgkmcnt(0)
	s_mov_b64 s[2:3], -1
	s_branch .LBB0_182

.LBB0_182:
	s_barrier
	ds_read_b128 v[48:51], v92 offset:48
	ds_read_b128 v[52:55], v92 offset:32
	ds_read_b128 v[56:59], v92 offset:16
	ds_read_b128 v[60:63], v92
	s_and_saveexec_b64 s[88:89], s[84:85]
	global_load_dwordx4 v[168:171], v[84:85], off offset:48
	global_load_dwordx4 v[172:175], v[84:85], off offset:32
	global_load_dwordx4 v[176:179], v[84:85], off offset:16
	global_load_dwordx4 v[196:199], v[84:85], off
	s_or_b64 exec, exec, s[88:89]
	s_waitcnt vmcnt(12)
	v_and_b32_e32 v159, 0xffff0000, v4
	v_lshlrev_b32_e32 v158, 16, v4
	v_and_b32_e32 v151, 0xffff0000, v5
	v_lshlrev_b32_e32 v150, 16, v5
	v_pk_mul_f32 v[162:163], v[158:159], v[158:159]
	v_pk_mul_f32 v[154:155], v[150:151], v[150:151]
	v_add_f32_e32 v108, v162, v163
	v_and_b32_e32 v145, 0xffff0000, v6
	v_lshlrev_b32_e32 v144, 16, v6
	v_add_f32_e32 v108, v154, v108
	v_pk_mul_f32 v[106:107], v[144:145], v[144:145]
	v_add_f32_e32 v108, v155, v108
	v_and_b32_e32 v101, 0xffff0000, v7
	v_lshlrev_b32_e32 v100, 16, v7
	v_add_f32_e32 v106, v106, v108
	v_pk_mul_f32 v[102:103], v[100:101], v[100:101]
	v_add_f32_e32 v106, v107, v106
	s_waitcnt vmcnt(8)
	v_and_b32_e32 v161, 0xffff0000, v12
	v_lshlrev_b32_e32 v160, 16, v12
	v_add_f32_e32 v102, v102, v106
	v_pk_mul_f32 v[164:165], v[160:161], v[160:161]
	v_add_f32_e32 v102, v103, v102
	v_and_b32_e32 v153, 0xffff0000, v13
	v_lshlrev_b32_e32 v152, 16, v13
	v_add_f32_e32 v102, v164, v102
	v_pk_mul_f32 v[156:157], v[152:153], v[152:153]
	v_add_f32_e32 v102, v165, v102
	v_and_b32_e32 v147, 0xffff0000, v14
	v_lshlrev_b32_e32 v146, 16, v14
	v_add_f32_e32 v102, v156, v102
	v_pk_mul_f32 v[148:149], v[146:147], v[146:147]
	v_add_f32_e32 v102, v157, v102
	v_and_b32_e32 v143, 0xffff0000, v15
	v_lshlrev_b32_e32 v142, 16, v15
	v_add_f32_e32 v102, v148, v102
	v_pk_mul_f32 v[104:105], v[142:143], v[142:143]
	v_add_f32_e32 v102, v149, v102
	v_add_f32_e32 v102, v104, v102
	v_lshlrev_b32_e32 v140, 16, v8
	v_add_f32_e32 v102, v105, v102
	v_and_b32_e32 v139, 0xffff0000, v8
	v_fmac_f32_e32 v102, v140, v140
	v_lshlrev_b32_e32 v138, 16, v9
	v_fmac_f32_e32 v102, v139, v139
	v_and_b32_e32 v137, 0xffff0000, v9
	v_fmac_f32_e32 v102, v138, v138
	v_lshlrev_b32_e32 v136, 16, v10
	v_fmac_f32_e32 v102, v137, v137
	v_and_b32_e32 v135, 0xffff0000, v10
	v_fmac_f32_e32 v102, v136, v136
	v_lshlrev_b32_e32 v134, 16, v11
	v_fmac_f32_e32 v102, v135, v135
	v_and_b32_e32 v99, 0xffff0000, v11
	v_and_b32_e32 v64, 0xffff0000, v16
	v_lshlrev_b32_e32 v65, 16, v16
	v_fmac_f32_e32 v102, v134, v134
	v_pk_mul_f32 v[72:73], v[64:65], v[64:65]
	v_fmac_f32_e32 v102, v99, v99
	v_and_b32_e32 v68, 0xffff0000, v17
	v_lshlrev_b32_e32 v69, 16, v17
	v_add_f32_e32 v73, v73, v102
	v_pk_mul_f32 v[74:75], v[68:69], v[68:69]
	v_add_f32_e32 v72, v72, v73
	v_and_b32_e32 v70, 0xffff0000, v18
	v_lshlrev_b32_e32 v71, 16, v18
	v_add_f32_e32 v72, v75, v72
	v_pk_mul_f32 v[76:77], v[70:71], v[70:71]
	v_add_f32_e32 v72, v74, v72
	v_and_b32_e32 v66, 0xffff0000, v19
	v_lshlrev_b32_e32 v67, 16, v19
	v_add_f32_e32 v72, v77, v72
	v_pk_mul_f32 v[78:79], v[66:67], v[66:67]
	v_add_f32_e32 v72, v76, v72
	v_add_f32_e32 v72, v79, v72
	v_add_f32_e32 v72, v78, v72
	s_nop 1
	s_waitcnt lgkmcnt(0)
	v_add_f32_dpp v72, v72, v72 quad_perm:[1,0,3,2] row_mask:0xf bank_mask:0xf
	v_fmamk_f32 v72, v72, 0x3c800000, v180
	v_rsq_f32_e32 v108, v72
	s_nop 0
	v_pk_mul_f32 v[72:73], v[108:109], v[158:159] op_sel_hi:[0,1]
	v_pk_mul_f32 v[106:107], v[60:61], v[72:73]
	v_pk_mul_f32 v[60:61], v[108:109], v[150:151] op_sel_hi:[0,1]
	v_pk_mul_f32 v[104:105], v[62:63], v[60:61]
	v_pk_mul_f32 v[60:61], v[108:109], v[144:145] op_sel_hi:[0,1]
	v_pk_mul_f32 v[102:103], v[56:57], v[60:61]
	v_pk_mul_f32 v[56:57], v[108:109], v[100:101] op_sel_hi:[0,1]
	v_pk_mul_f32 v[100:101], v[58:59], v[56:57]
	v_pk_mul_f32 v[56:57], v[108:109], v[160:161] op_sel_hi:[0,1]
	v_pk_mul_f32 v[78:79], v[52:53], v[56:57]
	v_pk_mul_f32 v[52:53], v[108:109], v[152:153] op_sel_hi:[0,1]
	v_pk_mul_f32 v[76:77], v[54:55], v[52:53]
	v_pk_mul_f32 v[52:53], v[108:109], v[146:147] op_sel_hi:[0,1]
	v_pk_mul_f32 v[74:75], v[48:49], v[52:53]
	v_pk_mul_f32 v[48:49], v[108:109], v[142:143] op_sel_hi:[0,1]
	v_pk_mul_f32 v[72:73], v[50:51], v[48:49]
	ds_read_b128 v[48:51], v92 offset:112
	ds_read_b128 v[52:55], v92 offset:96
	ds_read_b128 v[56:59], v92 offset:80
	ds_read_b128 v[60:63], v92 offset:64
	s_and_saveexec_b64 s[88:89], s[84:85]
	s_cbranch_execz .LBB0_184
	s_waitcnt vmcnt(0)
	v_mov_b64_e32 v[142:143], v[168:169]
	v_mov_b64_e32 v[144:145], v[170:171]
	v_mov_b64_e32 v[146:147], v[172:173]
	v_mov_b64_e32 v[148:149], v[174:175]
	v_mov_b64_e32 v[150:151], v[176:177]
	v_mov_b64_e32 v[152:153], v[178:179]
	v_mov_b64_e32 v[154:155], v[196:197]
	v_mov_b64_e32 v[156:157], v[198:199]
	v_pk_mul_f32 v[158:159], v[106:107], v[146:147]
	v_pk_mul_f32 v[146:147], v[78:79], v[146:147]
	v_pk_fma_f32 v[78:79], v[78:79], v[154:155], v[158:159]
	v_pk_fma_f32 v[106:107], v[106:107], v[154:155], v[146:147] neg_lo:[0,0,1] neg_hi:[0,0,1]
	v_pk_mul_f32 v[146:147], v[104:105], v[148:149]
	v_pk_mul_f32 v[148:149], v[76:77], v[148:149]
	v_pk_fma_f32 v[76:77], v[76:77], v[156:157], v[146:147]
	v_pk_mul_f32 v[146:147], v[102:103], v[142:143]
	v_pk_mul_f32 v[142:143], v[74:75], v[142:143]
	v_pk_fma_f32 v[104:105], v[104:105], v[156:157], v[148:149] neg_lo:[0,0,1] neg_hi:[0,0,1]
	v_pk_fma_f32 v[102:103], v[102:103], v[150:151], v[142:143] neg_lo:[0,0,1] neg_hi:[0,0,1]
	v_pk_mul_f32 v[142:143], v[100:101], v[144:145]
	v_pk_mul_f32 v[144:145], v[72:73], v[144:145]
	v_pk_fma_f32 v[74:75], v[74:75], v[150:151], v[146:147]
	v_pk_fma_f32 v[100:101], v[100:101], v[152:153], v[144:145] neg_lo:[0,0,1] neg_hi:[0,0,1]
	v_pk_fma_f32 v[72:73], v[72:73], v[152:153], v[142:143]
.LBB0_184:
	s_or_b64 exec, exec, s[88:89]
	v_mul_f32_e32 v64, v108, v64
	s_waitcnt lgkmcnt(2)
	v_mul_f32_e32 v53, v53, v64
	v_mul_f32_e32 v64, v108, v69
	v_mul_f32_e32 v54, v54, v64
	v_mul_f32_e32 v64, v108, v68
	v_mul_f32_e32 v55, v64, v55
	v_mul_f32_e32 v64, v108, v71
	v_mul_f32_e32 v65, v108, v65
	v_mul_f32_e32 v64, v64, v48
	v_mul_f32_e32 v48, v108, v70
	v_mul_f32_e32 v52, v52, v65
	v_mul_f32_e32 v65, v48, v49
	v_mul_f32_e32 v48, v108, v67
	v_mul_f32_e32 v67, v48, v50
	v_mul_f32_e32 v48, v108, v66
	v_mul_f32_e32 v66, v48, v51
	v_cvt_pk_bf16_f32 v48, v106, v107
	v_cvt_pk_bf16_f32 v49, v104, v105
	v_cvt_pk_bf16_f32 v50, v102, v103
	v_cvt_pk_bf16_f32 v51, v100, v101
	v_mul_f32_e32 v140, v108, v140
	v_mul_f32_e32 v139, v108, v139
	v_mul_f32_e32 v138, v108, v138
	v_mul_f32_e32 v137, v108, v137
	v_mul_f32_e32 v136, v108, v136
	v_mul_f32_e32 v135, v108, v135
	v_mul_f32_e32 v134, v108, v134
	v_mul_f32_e32 v99, v108, v99
	ds_write_b128 v115, v[48:51]
	v_cvt_pk_bf16_f32 v48, v78, v79
	v_cvt_pk_bf16_f32 v49, v76, v77
	v_cvt_pk_bf16_f32 v50, v74, v75
	v_cvt_pk_bf16_f32 v51, v72, v73
	s_waitcnt vmcnt(0) lgkmcnt(0)
	v_mul_f32_e32 v60, v60, v140
	v_mul_f32_e32 v61, v61, v139
	v_mul_f32_e32 v62, v62, v138
	v_mul_f32_e32 v63, v63, v137
	v_mul_f32_e32 v56, v56, v136
	v_mul_f32_e32 v57, v57, v135
	v_mul_f32_e32 v58, v58, v134
	v_mul_f32_e32 v59, v59, v99
	ds_write_b128 v115, v[48:51] offset:16
	v_cvt_pk_bf16_f32 v48, v60, v61
	v_cvt_pk_bf16_f32 v49, v62, v63
	v_cvt_pk_bf16_f32 v50, v56, v57
	v_cvt_pk_bf16_f32 v51, v58, v59
	ds_write_b128 v115, v[48:51] offset:32
	v_cvt_pk_bf16_f32 v48, v52, v53
	v_cvt_pk_bf16_f32 v49, v54, v55
	v_cvt_pk_bf16_f32 v50, v64, v65
	v_cvt_pk_bf16_f32 v51, v67, v66
	s_andn2_b64 vcc, exec, s[2:3]
	ds_write_b128 v115, v[48:51] offset:48
	ds_write_b16 v116, v24 offset:36864
	ds_write_b16_d16_hi v116, v24 offset:37392
	ds_write_b16 v116, v25 offset:37920
	ds_write_b16_d16_hi v116, v25 offset:38448
	ds_write_b16 v116, v26 offset:38976
	ds_write_b16_d16_hi v116, v26 offset:39504
	ds_write_b16 v116, v27 offset:40032
	ds_write_b16_d16_hi v116, v27 offset:40560
	ds_write_b16 v116, v28 offset:41088
	ds_write_b16_d16_hi v116, v28 offset:41616
	ds_write_b16 v116, v29 offset:42144
	ds_write_b16_d16_hi v116, v29 offset:42672
	ds_write_b16 v116, v30 offset:43200
	ds_write_b16_d16_hi v116, v30 offset:43728
	ds_write_b16 v116, v31 offset:44256
	ds_write_b16_d16_hi v116, v31 offset:44784
	ds_write_b16 v116, v32 offset:45312
	ds_write_b16_d16_hi v116, v32 offset:45840
	ds_write_b16 v116, v33 offset:46368
	ds_write_b16_d16_hi v116, v33 offset:46896
	ds_write_b16 v116, v34 offset:47424
	ds_write_b16_d16_hi v116, v34 offset:47952
	ds_write_b16 v116, v35 offset:48480
	ds_write_b16_d16_hi v116, v35 offset:49008
	ds_write_b16 v116, v20 offset:49536
	ds_write_b16_d16_hi v116, v20 offset:50064
	ds_write_b16 v116, v21 offset:50592
	ds_write_b16_d16_hi v116, v21 offset:51120
	ds_write_b16 v116, v22 offset:51648
	ds_write_b16_d16_hi v116, v22 offset:52176
	ds_write_b16 v116, v23 offset:52704
	ds_write_b16_d16_hi v116, v23 offset:53232
	s_waitcnt lgkmcnt(0)
	s_barrier
	s_cbranch_vccnz .LBB0_188
	v_readlane_b32 s4, v243, 10
	v_mov_b32_e32 v23, 0
	v_mov_b32_e32 v19, 0
	v_mov_b32_e32 v18, 0
	v_mov_b32_e32 v17, 0
	v_mov_b32_e32 v16, 0
	v_mov_b32_e32 v11, 0
	v_mov_b32_e32 v10, 0
	v_mov_b32_e32 v9, 0
	v_mov_b32_e32 v8, 0
	v_mov_b32_e32 v15, 0
	v_mov_b32_e32 v14, 0
	v_mov_b32_e32 v13, 0
	v_mov_b32_e32 v12, 0
	v_mov_b32_e32 v7, 0
	v_mov_b32_e32 v6, 0
	v_mov_b32_e32 v5, 0
	v_mov_b32_e32 v4, 0
	v_mov_b32_e32 v22, 0
	v_mov_b32_e32 v21, 0
	v_mov_b32_e32 v20, 0
	v_mov_b32_e32 v35, 0
	v_mov_b32_e32 v34, 0
	v_mov_b32_e32 v33, 0
	v_mov_b32_e32 v32, 0
	v_mov_b32_e32 v31, 0
	v_mov_b32_e32 v30, 0
	v_mov_b32_e32 v29, 0
	v_mov_b32_e32 v28, 0
	v_mov_b32_e32 v27, 0
	v_mov_b32_e32 v26, 0
	v_mov_b32_e32 v25, 0
	v_mov_b32_e32 v24, 0
	v_readlane_b32 s5, v243, 11
	s_and_saveexec_b64 s[88:89], s[4:5]
	s_cbranch_execz .LBB0_187
	global_load_dwordx4 v[4:7], v[88:89], off
	global_load_dwordx4 v[12:15], v[88:89], off offset:16
	global_load_dwordx4 v[8:11], v[88:89], off offset:32
	global_load_dwordx4 v[16:19], v[88:89], off offset:48
	global_load_dwordx4 v[24:27], v[86:87], off
	global_load_dwordx4 v[28:31], v[86:87], off offset:16
	global_load_dwordx4 v[32:35], v[86:87], off offset:32
	global_load_dwordx4 v[20:23], v[86:87], off offset:48
